# v102 + rwkv_p3 (barrier-free, one wave per item half): waves 4-7 start ~1000 cycles late so SIMD partners alternate load waits with MFMA/group-norm work
# baseline (speedup 1.0000x reference)
;     __device__ __forceinline__ unsigned char* ws() const { return *(const __attribute__((address_space(4))) ucptr_t*)(p + 264); }
; __device__ __forceinline__ void rwkv_p3(const KA& A, const Ctx& F) {
;     ...
;     const int lane = F.lane, w = F.wave, r32 = lane & 31, hh = lane >> 5, tb2 = w & 1;
; #pragma unroll 1
;     for (int it4 = F.bid; it4 < RW_ITEMS / 4; it4 += F.G) {
;         const int item = (RW_ITEMS / 4 - 1 - it4) * 4 + (w >> 1); const int j = item & 63, h = (item >> 6) % 6, b = item / 384;
;         const size_t row0 = (size_t)b * SEQ + 64 * j;
;         const int t = 32 * tb2 + r32;
;         const bf16* qd = PS + (row0 + t) * PSW + C_RW + h * 64; const bf16* yd = qd + 384; const bf16* ed = qd + 768; const bf16* EM = (const bf16*)(F.ws + WS_REM) + (size_t)item * 4096 + t * 64;
;         const bf16* HS = (const bf16*)(F.ws + WS_RHS) + (size_t)item * 4096;
.LBB0_162:
	v_mov_b32_e32 v0, v242
	s_cmpk_gt_i32 s80, 0x2ff
	v_readfirstlane_b32 s0, v0
	s_cbranch_scc1 .LBB0_165
	v_and_b32_e32 v1, 31, v0
	s_ashr_i32 s2, s0, 7
	s_cmp_lt_u32 s2, 2
	s_cbranch_scc1 .Lp3_nostag
	s_sleep 16
.Lp3_nostag:
	s_lshr_b32 s0, s0, 1
	v_and_or_b32 v64, s0, 32, v1
	v_readlane_b32 s4, v253, 60
	v_lshrrev_b32_e32 v1, 2, v0
	v_lshlrev_b32_e32 v80, 7, v64
	v_readlane_b32 s6, v253, 62
	v_readlane_b32 s7, v253, 63
	v_lshlrev_b32_e32 v0, 4, v0
	v_and_b32_e32 v2, 8, v1
	v_lshl_add_u64 v[4:5], s[6:7], 0, v[80:81]
	v_and_b32_e32 v80, 0x3f0, v0
	v_lshl_add_u64 v[66:67], s[28:29], 0, v[80:81]
	v_lshlrev_b32_e32 v80, 1, v2
	v_lshl_add_u64 v[0:1], v[4:5], 0, v[80:81]
	s_mov_b64 s[0:1], 0x1d800000
	v_lshl_add_u64 v[68:69], v[0:1], 0, s[0:1]
	s_and_b32 s1, s80, 7
	s_sub_i32 s1, 7, s1
	s_mulk_i32 s1, 0x60
	s_lshr_b32 s0, s80, 3
	s_add_i32 s1, s1, s0
	s_lshl_b32 s0, s1, 2
	s_sub_i32 s0, s2, s0
	v_readlane_b32 s5, v253, 61
	s_addk_i32 s0, 0xbfc
	s_movk_i32 s2, 0x80
	s_lshl_b32 s3, s0, 6
	s_movk_i32 s4, 0x2000
	v_lshlrev_b32_e32 v80, 1, v2
	s_mov_b32 s5, s80
